# bundle: write-through partial-sum phases without L2 write-back at their barriers + prompt softmax exp pass folded to one fma per element
# baseline (speedup 1.0000x reference)
.LBB0_985:
	s_mov_b32 s101, 0x3db8aa3b
	s_mov_b32 s99, 0x20400
	v_mov_b32_e32 v14, v136
	s_barrier
	s_ashr_i32 s33, s47, 5
	v_bfe_i32 v2, v14, 27, 1
	v_lshlrev_b32_e32 v1, 4, v14
	v_lshrrev_b32_e32 v2, 22, v2
	v_add_u32_e32 v2, v1, v2
	v_and_b32_e32 v2, 0xfffffc00, v2
	v_sub_u32_e32 v2, v1, v2
	v_lshrrev_b32_e32 v3, 4, v2
	v_ashrrev_i32_e32 v0, 31, v14
	v_bitop3_b32 v2, v3, v2, 32 bitop3:0x6c
	v_lshrrev_b32_e32 v0, 26, v0
	v_ashrrev_i32_e32 v4, 31, v2
	v_add_u32_e32 v0, v14, v0
	v_lshrrev_b32_e32 v4, 26, v4
	v_ashrrev_i32_e32 v0, 6, v0
	v_add_u32_e32 v4, v2, v4
	v_lshlrev_b32_e32 v3, 3, v0
	v_ashrrev_i32_e32 v5, 6, v4
	v_and_b32_e32 v4, 0xc0, v4
	v_and_b32_e32 v3, -16, v3
	v_lshlrev_b32_e32 v0, 5, v0
	v_sub_u32_e32 v2, v2, v4
	v_add_u32_e32 v3, v5, v3
	v_and_b32_e32 v0, 32, v0
	v_ashrrev_i16_sdwa v2, v133, sext(v2) dst_sel:DWORD dst_unused:UNUSED_PAD src0_sel:DWORD src1_sel:BYTE_0
	v_add_u32_sdwa v0, v0, sext(v2) dst_sel:DWORD dst_unused:UNUSED_PAD src0_sel:DWORD src1_sel:WORD_0
	v_lshlrev_b32_e32 v2, 11, v3
	v_lshl_add_u32 v0, v0, 1, v2
	v_mad_u64_u32 v[6:7], s[52:53], v3, s37, v[0:1]
	v_add_u32_e32 v1, 0x2000, v1
	v_ashrrev_i32_e32 v2, 31, v1
	v_lshrrev_b32_e32 v2, 22, v2
	v_add_u32_e32 v2, v1, v2
	v_ashrrev_i32_e32 v2, 10, v2
	s_lshl_b32 s26, s33, 11
	s_and_b32 s27, s3, 0x700
	v_mul_i32_i24_e32 v3, 0x400, v2
	s_or_b32 s26, s26, s27
	v_sub_u32_e32 v1, v1, v3
	s_ashr_i32 s27, s26, 31
	v_lshrrev_b32_e32 v3, 4, v1
	s_bfe_u32 s50, s47, 0x20003
	s_lshl_b64 s[28:29], s[26:27], 11
	v_bitop3_b32 v1, v3, v1, 32 bitop3:0x6c
	s_add_u32 s27, s62, s28
	v_ashrrev_i32_e32 v4, 31, v1
	s_addc_u32 s28, s63, s29
	s_lshl_b32 s29, s50, 9
	v_lshrrev_b32_e32 v4, 26, v4
	s_add_u32 s30, s27, s29
	v_add_u32_e32 v4, v1, v4
	s_addc_u32 s31, s28, 0
	s_lshl_b32 s27, s33, 2
	v_lshlrev_b32_e32 v3, 3, v2
	v_ashrrev_i32_e32 v5, 6, v4
	v_and_b32_e32 v4, 0xc0, v4
	s_or_b32 s28, s27, s50
	v_and_b32_e32 v3, -16, v3
	v_lshlrev_b32_e32 v2, 5, v2
	v_sub_u32_e32 v1, v1, v4
	s_ashr_i32 s29, s28, 31
	v_add_u32_e32 v3, v5, v3
	v_and_b32_e32 v2, 32, v2
	v_ashrrev_i16_sdwa v1, v133, sext(v1) dst_sel:DWORD dst_unused:UNUSED_PAD src0_sel:DWORD src1_sel:BYTE_0
	s_lshl_b64 s[34:35], s[28:29], 17
	v_add_u32_sdwa v1, v2, sext(v1) dst_sel:DWORD dst_unused:UNUSED_PAD src0_sel:DWORD src1_sel:WORD_0
	v_lshlrev_b32_e32 v2, 11, v3
	s_add_u32 s34, s64, s34
	v_readfirstlane_b32 s27, v14
	v_lshl_add_u32 v2, v1, 1, v2
	s_addc_u32 s35, s65, s35
	v_mad_u64_u32 v[4:5], s[52:53], v3, s37, v[2:3]
	s_ashr_i32 s51, s27, 6
	s_lshl_b32 s53, s51, 10
	s_add_i32 s76, s53, 0
	s_add_i32 m0, s76, 0x10000
	s_ashr_i32 s33, s27, 8
	global_load_lds_dwordx4 v6, s[34:35]
	s_add_i32 m0, s76, 0x12000
	s_add_i32 s77, s76, 0x2000
	global_load_lds_dwordx4 v4, s[34:35]
	s_mov_b32 m0, s76
	s_add_u32 s56, s34, 0x10000
	global_load_lds_dwordx4 v0, s[30:31]
	s_mov_b32 m0, s77
	s_addc_u32 s57, s35, 0
	global_load_lds_dwordx4 v2, s[30:31]
	s_add_i32 m0, s76, 0x14000
	v_mov_b32_e32 v128, v6
	global_load_lds_dwordx4 v6, s[56:57]
	s_add_i32 m0, s76, 0x16000
	s_add_u32 s72, s30, 0x40000
	global_load_lds_dwordx4 v4, s[56:57]
	s_addc_u32 s73, s31, 0
	s_add_i32 s57, s76, 0x4000
	s_mov_b32 m0, s57
	s_add_i32 s52, s76, 0x6000
	global_load_lds_dwordx4 v0, s[72:73]
	s_mov_b32 m0, s52
	v_mov_b32_e32 v5, v129
	global_load_lds_dwordx4 v2, s[72:73]
	v_mov_b32_e32 v1, v129
	v_mov_b32_e32 v3, v129
	v_lshl_add_u64 v[12:13], s[34:35], 0, v[128:129]
	v_lshl_add_u64 v[10:11], s[34:35], 0, v[4:5]
	v_lshl_add_u64 v[6:7], s[30:31], 0, v[0:1]
	s_cmp_lg_u32 s33, 1
	v_lshl_add_u64 v[8:9], s[30:31], 0, v[2:3]
	s_cbranch_scc1 .LBB0_987
	s_barrier

.LBB0_1005:
	s_or_b64 exec, exec, s[30:31]
	v_add3_u32 v134, s99, v130, v131
	v_add_u32_e32 v142, 0xc00, v134
	s_waitcnt vmcnt(0) lgkmcnt(0)
	s_barrier
	ds_read2_b32 v[160:161], v134 offset1:16
	v_add_u32_e32 v140, 0x800, v134
	ds_read2_b32 v[166:167], v142 offset1:16
	ds_read2_b32 v[164:165], v140 offset1:16
	v_add_u32_e32 v138, 0x400, v134
	ds_read2_b32 v[162:163], v138 offset1:16
	ds_read2_b32 v[152:153], v134 offset0:32 offset1:48
	ds_read2_b32 v[154:155], v138 offset0:32 offset1:48
	ds_read2_b32 v[156:157], v140 offset0:32 offset1:48
	ds_read2_b32 v[158:159], v142 offset0:32 offset1:48
	ds_read2_b32 v[144:145], v134 offset0:128 offset1:144
	ds_read2_b32 v[146:147], v138 offset0:128 offset1:144
	ds_read2_b32 v[148:149], v140 offset0:128 offset1:144
	ds_read2_b32 v[150:151], v142 offset0:128 offset1:144
	s_waitcnt lgkmcnt(10)
	v_max_f32_e32 v130, v166, v166
	s_waitcnt lgkmcnt(9)
	v_max_f32_e32 v131, v164, v164
	v_max_f32_e32 v130, v131, v130
	s_waitcnt lgkmcnt(8)
	v_max3_f32 v135, v160, v162, v130
	v_mul_f32_e32 v135, 0xbdb8aa3b, v135
	v_fma_f32 v124, v124, s101, v135
	v_fma_f32 v125, v125, s101, v135
	v_fma_f32 v126, v126, s101, v135
	v_exp_f32_e32 v124, v124
	v_fma_f32 v127, v127, s101, v135
	v_exp_f32_e32 v125, v125
	v_exp_f32_e32 v126, v126
	v_exp_f32_e32 v127, v127
	v_add_f32_e32 v130, 0, v124
	v_fma_f32 v116, v116, s101, v135
	v_fma_f32 v118, v118, s101, v135
	v_add_f32_e32 v130, v125, v130
	v_fma_f32 v117, v117, s101, v135
	v_add_f32_e32 v130, v126, v130
	v_add_f32_e32 v139, v127, v130
	v_exp_f32_e32 v116, v116
	v_exp_f32_e32 v130, v118
	v_fma_f32 v118, v119, s101, v135
	v_exp_f32_e32 v117, v117
	v_exp_f32_e32 v131, v118
	v_add_f32_e32 v118, v116, v139
	v_add_f32_e32 v118, v117, v118
	v_add_f32_e32 v118, v130, v118
	v_add_f32_e32 v139, v131, v118
	v_fma_f32 v118, v120, s101, v135
	v_fma_f32 v119, v121, s101, v135
	v_fma_f32 v120, v122, s101, v135
	v_exp_f32_e32 v118, v118
	v_fma_f32 v121, v123, s101, v135
	v_exp_f32_e32 v119, v119
	v_fma_f32 v112, v112, s101, v135
	v_exp_f32_e32 v120, v120
	v_fma_f32 v113, v113, s101, v135
	v_exp_f32_e32 v121, v121
	v_fma_f32 v114, v114, s101, v135
	v_add_f32_e32 v122, v118, v139
	v_exp_f32_e32 v112, v112
	v_fma_f32 v115, v115, s101, v135
	v_add_f32_e32 v122, v119, v122
	v_exp_f32_e32 v113, v113
	v_add_f32_e32 v122, v120, v122
	v_exp_f32_e32 v114, v114
	v_add_f32_e32 v122, v121, v122
	v_exp_f32_e32 v115, v115
	v_add_f32_e32 v122, v112, v122
	v_add_f32_e32 v122, v113, v122
	v_add_f32_e32 v122, v114, v122
	v_add_f32_e32 v122, v115, v122
	ds_bpermute_b32 v123, v171, v122
	ds_read2_b32 v[134:135], v134 offset0:160 offset1:176
	ds_read2_b32 v[138:139], v138 offset0:160 offset1:176
	ds_read2_b32 v[140:141], v140 offset0:160 offset1:176
	ds_read2_b32 v[142:143], v142 offset0:160 offset1:176
	s_waitcnt lgkmcnt(0)
	s_barrier
	v_add_f32_e32 v122, v122, v123
	ds_bpermute_b32 v123, v172, v122
	s_and_saveexec_b64 s[30:31], vcc
	s_cbranch_execz .LBB0_1007
	s_waitcnt lgkmcnt(0)
	v_add_f32_e32 v122, v122, v123
	ds_write_b32 v173, v122
.LBB0_1007:
	s_or_b64 exec, exec, s[30:31]
	v_max_f32_e32 v122, v167, v167
	s_waitcnt lgkmcnt(0)
	v_max_f32_e32 v123, v165, v165
	v_max_f32_e32 v122, v123, v122
	v_max3_f32 v160, v161, v163, v122
	v_mul_f32_e32 v160, 0xbdb8aa3b, v160
	v_fma_f32 v108, v108, s101, v160
	v_fma_f32 v109, v109, s101, v160
	v_fma_f32 v110, v110, s101, v160
	v_exp_f32_e32 v108, v108
	v_fma_f32 v111, v111, s101, v160
	v_exp_f32_e32 v109, v109
	v_exp_f32_e32 v110, v110
	v_exp_f32_e32 v111, v111
	v_add_f32_e32 v122, 0, v108
	v_fma_f32 v100, v100, s101, v160
	v_fma_f32 v102, v102, s101, v160
	v_add_f32_e32 v122, v109, v122
	v_fma_f32 v101, v101, s101, v160
	v_add_f32_e32 v122, v110, v122
	v_add_f32_e32 v161, v111, v122
	v_exp_f32_e32 v100, v100
	v_exp_f32_e32 v122, v102
	v_fma_f32 v102, v103, s101, v160
	v_exp_f32_e32 v101, v101
	v_exp_f32_e32 v123, v102
	v_add_f32_e32 v102, v100, v161
	v_add_f32_e32 v102, v101, v102
	v_add_f32_e32 v102, v122, v102
	v_add_f32_e32 v161, v123, v102
	v_fma_f32 v102, v104, s101, v160
	v_fma_f32 v103, v105, s101, v160
	v_fma_f32 v104, v106, s101, v160
	v_exp_f32_e32 v102, v102
	v_fma_f32 v105, v107, s101, v160
	v_exp_f32_e32 v103, v103
	v_fma_f32 v96, v96, s101, v160
	v_exp_f32_e32 v104, v104
	v_fma_f32 v97, v97, s101, v160
	v_exp_f32_e32 v105, v105
	v_fma_f32 v98, v98, s101, v160
	v_add_f32_e32 v106, v102, v161
	v_exp_f32_e32 v96, v96
	v_fma_f32 v99, v99, s101, v160
	v_add_f32_e32 v106, v103, v106
	v_exp_f32_e32 v97, v97
	v_add_f32_e32 v106, v104, v106
	v_exp_f32_e32 v98, v98
	v_add_f32_e32 v106, v105, v106
	v_exp_f32_e32 v99, v99
	v_add_f32_e32 v106, v96, v106
	v_add_f32_e32 v106, v97, v106
	v_add_f32_e32 v106, v98, v106
	v_add_f32_e32 v106, v99, v106
	ds_bpermute_b32 v107, v171, v106
	s_waitcnt lgkmcnt(0)
	v_add_f32_e32 v106, v106, v107
	ds_bpermute_b32 v107, v172, v106
	s_and_saveexec_b64 s[30:31], vcc
	s_cbranch_execz .LBB0_1009
	s_waitcnt lgkmcnt(0)
	v_add_f32_e32 v106, v106, v107
	ds_write_b32 v173, v106 offset:64
.LBB0_1009:
	s_or_b64 exec, exec, s[30:31]
	v_max_f32_e32 v106, v158, v158
	s_waitcnt lgkmcnt(0)
	v_max_f32_e32 v107, v156, v156
	v_max_f32_e32 v106, v107, v106
	v_max3_f32 v152, v152, v154, v106
	v_mul_f32_e32 v152, 0xbdb8aa3b, v152
	v_fma_f32 v92, v92, s101, v152
	v_fma_f32 v93, v93, s101, v152
	v_fma_f32 v94, v94, s101, v152
	v_exp_f32_e32 v92, v92
	v_fma_f32 v95, v95, s101, v152
	v_exp_f32_e32 v93, v93
	v_exp_f32_e32 v94, v94
	v_exp_f32_e32 v95, v95
	v_add_f32_e32 v106, 0, v92
	v_fma_f32 v84, v84, s101, v152
	v_fma_f32 v86, v86, s101, v152
	v_add_f32_e32 v106, v93, v106
	v_fma_f32 v85, v85, s101, v152
	v_add_f32_e32 v106, v94, v106
	v_add_f32_e32 v154, v95, v106
	v_exp_f32_e32 v84, v84
	v_exp_f32_e32 v106, v86
	v_fma_f32 v86, v87, s101, v152
	v_exp_f32_e32 v85, v85
	v_exp_f32_e32 v107, v86
	v_add_f32_e32 v86, v84, v154
	v_add_f32_e32 v86, v85, v86
	v_add_f32_e32 v86, v106, v86
	v_add_f32_e32 v154, v107, v86
	v_fma_f32 v86, v88, s101, v152
	v_fma_f32 v87, v89, s101, v152
	v_fma_f32 v88, v90, s101, v152
	v_exp_f32_e32 v86, v86
	v_fma_f32 v89, v91, s101, v152
	v_exp_f32_e32 v87, v87
	v_fma_f32 v80, v80, s101, v152
	v_exp_f32_e32 v88, v88
	v_fma_f32 v81, v81, s101, v152
	v_exp_f32_e32 v89, v89
	v_fma_f32 v82, v82, s101, v152
	v_add_f32_e32 v90, v86, v154
	v_exp_f32_e32 v80, v80
	v_fma_f32 v83, v83, s101, v152
	v_add_f32_e32 v90, v87, v90
	v_exp_f32_e32 v81, v81
	v_add_f32_e32 v90, v88, v90
	v_exp_f32_e32 v82, v82
	v_add_f32_e32 v90, v89, v90
	v_exp_f32_e32 v83, v83
	v_add_f32_e32 v90, v80, v90
	v_add_f32_e32 v90, v81, v90
	v_add_f32_e32 v90, v82, v90
	v_add_f32_e32 v90, v83, v90
	ds_bpermute_b32 v91, v171, v90
	s_waitcnt lgkmcnt(0)
	v_add_f32_e32 v90, v90, v91
	ds_bpermute_b32 v91, v172, v90
	s_and_saveexec_b64 s[30:31], vcc
	s_cbranch_execz .LBB0_1011
	s_waitcnt lgkmcnt(0)
	v_add_f32_e32 v90, v90, v91
	ds_write_b32 v173, v90 offset:128
.LBB0_1011:
	s_or_b64 exec, exec, s[30:31]
	v_max_f32_e32 v90, v159, v159
	s_waitcnt lgkmcnt(0)
	v_max_f32_e32 v91, v157, v157
	v_max_f32_e32 v90, v91, v90
	v_max3_f32 v152, v153, v155, v90
	v_mul_f32_e32 v152, 0xbdb8aa3b, v152
	v_fma_f32 v76, v76, s101, v152
	v_fma_f32 v77, v77, s101, v152
	v_fma_f32 v78, v78, s101, v152
	v_exp_f32_e32 v76, v76
	v_fma_f32 v79, v79, s101, v152
	v_exp_f32_e32 v77, v77
	v_exp_f32_e32 v78, v78
	v_exp_f32_e32 v79, v79
	v_add_f32_e32 v90, 0, v76
	v_fma_f32 v68, v68, s101, v152
	v_fma_f32 v70, v70, s101, v152
	v_add_f32_e32 v90, v77, v90
	v_fma_f32 v69, v69, s101, v152
	v_add_f32_e32 v90, v78, v90
	v_add_f32_e32 v153, v79, v90
	v_exp_f32_e32 v68, v68
	v_exp_f32_e32 v90, v70
	v_fma_f32 v70, v71, s101, v152
	v_exp_f32_e32 v69, v69
	v_exp_f32_e32 v91, v70
	v_add_f32_e32 v70, v68, v153
	v_add_f32_e32 v70, v69, v70
	v_add_f32_e32 v70, v90, v70
	v_add_f32_e32 v153, v91, v70
	v_fma_f32 v70, v72, s101, v152
	v_fma_f32 v72, v74, s101, v152
	v_fma_f32 v71, v73, s101, v152
	v_exp_f32_e32 v70, v70
	v_exp_f32_e32 v74, v72
	v_fma_f32 v72, v75, s101, v152
	v_exp_f32_e32 v71, v71
	v_exp_f32_e32 v75, v72
	v_add_f32_e32 v72, v70, v153
	v_fma_f32 v64, v64, s101, v152
	v_add_f32_e32 v72, v71, v72
	v_add_f32_e32 v72, v74, v72
	v_add_f32_e32 v153, v75, v72
	v_exp_f32_e32 v72, v64
	v_fma_f32 v64, v65, s101, v152
	v_exp_f32_e32 v73, v64
	v_fma_f32 v64, v66, s101, v152
	v_exp_f32_e32 v66, v64
	v_fma_f32 v64, v67, s101, v152
	v_exp_f32_e32 v67, v64
	v_add_f32_e32 v64, v72, v153
	v_add_f32_e32 v64, v73, v64
	v_add_f32_e32 v64, v66, v64
	v_add_f32_e32 v64, v67, v64
	ds_bpermute_b32 v65, v171, v64
	s_waitcnt lgkmcnt(0)
	v_add_f32_e32 v64, v64, v65
	ds_bpermute_b32 v65, v172, v64
	s_and_saveexec_b64 s[30:31], vcc
	s_cbranch_execz .LBB0_1013
	s_waitcnt lgkmcnt(0)
	v_add_f32_e32 v64, v64, v65
	ds_write_b32 v173, v64 offset:192
.LBB0_1013:
	s_or_b64 exec, exec, s[30:31]
	v_max_f32_e32 v64, v150, v150
	s_waitcnt lgkmcnt(0)
	v_max_f32_e32 v65, v148, v148
	v_max_f32_e32 v64, v65, v64
	v_max3_f32 v144, v144, v146, v64
	v_mul_f32_e32 v144, 0xbdb8aa3b, v144
	v_fma_f32 v60, v60, s101, v144
	v_fma_f32 v61, v61, s101, v144
	v_fma_f32 v62, v62, s101, v144
	v_exp_f32_e32 v60, v60
	v_fma_f32 v63, v63, s101, v144
	v_exp_f32_e32 v61, v61
	v_fma_f32 v56, v56, s101, v144
	v_exp_f32_e32 v62, v62
	v_fma_f32 v57, v57, s101, v144
	v_exp_f32_e32 v63, v63
	v_fma_f32 v58, v58, s101, v144
	v_add_f32_e32 v64, 0, v60
	v_exp_f32_e32 v56, v56
	v_fma_f32 v59, v59, s101, v144
	v_add_f32_e32 v64, v61, v64
	v_exp_f32_e32 v57, v57
	v_add_f32_e32 v64, v62, v64
	v_exp_f32_e32 v58, v58
	v_add_f32_e32 v64, v63, v64
	v_exp_f32_e32 v59, v59
	v_add_f32_e32 v64, v56, v64
	v_fma_f32 v52, v52, s101, v144
	v_fma_f32 v54, v54, s101, v144
	v_add_f32_e32 v64, v57, v64
	v_fma_f32 v53, v53, s101, v144
	v_add_f32_e32 v64, v58, v64
	v_add_f32_e32 v146, v59, v64
	v_exp_f32_e32 v52, v52
	v_exp_f32_e32 v64, v54
	v_fma_f32 v54, v55, s101, v144
	v_exp_f32_e32 v53, v53
	v_exp_f32_e32 v65, v54
	v_add_f32_e32 v54, v52, v146
	v_fma_f32 v48, v48, s101, v144
	v_add_f32_e32 v54, v53, v54
	v_add_f32_e32 v54, v64, v54
	v_add_f32_e32 v146, v65, v54
	v_exp_f32_e32 v54, v48
	v_fma_f32 v48, v49, s101, v144
	v_exp_f32_e32 v55, v48
	v_fma_f32 v48, v50, s101, v144
	v_exp_f32_e32 v50, v48
	v_fma_f32 v48, v51, s101, v144
	v_exp_f32_e32 v51, v48
	v_add_f32_e32 v48, v54, v146
	v_add_f32_e32 v48, v55, v48
	v_add_f32_e32 v48, v50, v48
	v_add_f32_e32 v48, v51, v48
	ds_bpermute_b32 v49, v171, v48
	s_waitcnt lgkmcnt(0)
	v_add_f32_e32 v48, v48, v49
	ds_bpermute_b32 v49, v172, v48
	s_and_saveexec_b64 s[30:31], vcc
	s_cbranch_execz .LBB0_1015
	s_waitcnt lgkmcnt(0)
	v_add_f32_e32 v48, v48, v49
	ds_write_b32 v173, v48 offset:512
.LBB0_1015:
	s_or_b64 exec, exec, s[30:31]
	v_max_f32_e32 v48, v151, v151
	s_waitcnt lgkmcnt(0)
	v_max_f32_e32 v49, v149, v149
	v_max_f32_e32 v48, v49, v48
	v_max3_f32 v49, v145, v147, v48
	v_mul_f32_e32 v49, 0xbdb8aa3b, v49
	v_fma_f32 v44, v44, s101, v49
	v_fma_f32 v45, v45, s101, v49
	v_fma_f32 v46, v46, s101, v49
	v_exp_f32_e32 v44, v44
	v_fma_f32 v47, v47, s101, v49
	v_exp_f32_e32 v45, v45
	v_fma_f32 v40, v40, s101, v49
	v_exp_f32_e32 v46, v46
	v_fma_f32 v41, v41, s101, v49
	v_exp_f32_e32 v47, v47
	v_fma_f32 v42, v42, s101, v49
	v_add_f32_e32 v48, 0, v44
	v_exp_f32_e32 v40, v40
	v_fma_f32 v43, v43, s101, v49
	v_add_f32_e32 v48, v45, v48
	v_exp_f32_e32 v41, v41
	v_fma_f32 v36, v36, s101, v49
	v_add_f32_e32 v48, v46, v48
	v_exp_f32_e32 v42, v42
	v_fma_f32 v37, v37, s101, v49
	v_add_f32_e32 v48, v47, v48
	v_exp_f32_e32 v43, v43
	v_fma_f32 v38, v38, s101, v49
	v_add_f32_e32 v48, v40, v48
	v_exp_f32_e32 v36, v36
	v_fma_f32 v39, v39, s101, v49
	v_add_f32_e32 v48, v41, v48
	v_exp_f32_e32 v37, v37
	v_add_f32_e32 v48, v42, v48
	v_exp_f32_e32 v38, v38
	v_add_f32_e32 v48, v43, v48
	v_exp_f32_e32 v39, v39
	v_add_f32_e32 v48, v36, v48
	v_fma_f32 v32, v32, s101, v49
	v_fma_f32 v34, v34, s101, v49
	v_add_f32_e32 v48, v37, v48
	v_fma_f32 v33, v33, s101, v49
	v_add_f32_e32 v48, v38, v48
	v_add_f32_e32 v144, v39, v48
	v_exp_f32_e32 v32, v32
	v_exp_f32_e32 v48, v34
	v_fma_f32 v34, v35, s101, v49
	v_exp_f32_e32 v33, v33
	v_exp_f32_e32 v49, v34
	v_add_f32_e32 v34, v32, v144
	v_add_f32_e32 v34, v33, v34
	v_add_f32_e32 v34, v48, v34
	v_add_f32_e32 v34, v49, v34
	ds_bpermute_b32 v35, v171, v34
	s_waitcnt lgkmcnt(0)
	v_add_f32_e32 v34, v34, v35
	ds_bpermute_b32 v35, v172, v34
	s_and_saveexec_b64 s[30:31], vcc
	s_cbranch_execz .LBB0_1017
	s_waitcnt lgkmcnt(0)
	v_add_f32_e32 v34, v34, v35
	ds_write_b32 v173, v34 offset:576
.LBB0_1017:
	s_or_b64 exec, exec, s[30:31]
	v_max_f32_e32 v34, v142, v142
	s_waitcnt lgkmcnt(0)
	v_max_f32_e32 v35, v140, v140
	v_max_f32_e32 v34, v35, v34
	v_max3_f32 v34, v134, v138, v34
	v_mul_f32_e32 v34, 0xbdb8aa3b, v34
	v_fma_f32 v28, v28, s101, v34
	v_fma_f32 v29, v29, s101, v34
	v_fma_f32 v30, v30, s101, v34
	v_exp_f32_e32 v28, v28
	v_fma_f32 v31, v31, s101, v34
	v_exp_f32_e32 v29, v29
	v_fma_f32 v24, v24, s101, v34
	v_exp_f32_e32 v30, v30
	v_fma_f32 v25, v25, s101, v34
	v_exp_f32_e32 v31, v31
	v_fma_f32 v26, v26, s101, v34
	v_add_f32_e32 v35, 0, v28
	v_exp_f32_e32 v24, v24
	v_fma_f32 v27, v27, s101, v34
	v_add_f32_e32 v35, v29, v35
	v_exp_f32_e32 v25, v25
	v_fma_f32 v20, v20, s101, v34
	v_add_f32_e32 v35, v30, v35
	v_exp_f32_e32 v26, v26
	v_fma_f32 v21, v21, s101, v34
	v_add_f32_e32 v35, v31, v35
	v_exp_f32_e32 v27, v27
	v_fma_f32 v22, v22, s101, v34
	v_add_f32_e32 v35, v24, v35
	v_exp_f32_e32 v20, v20
	v_fma_f32 v23, v23, s101, v34
	v_add_f32_e32 v35, v25, v35
	v_exp_f32_e32 v21, v21
	v_fma_f32 v16, v16, s101, v34
	v_add_f32_e32 v35, v26, v35
	v_exp_f32_e32 v22, v22
	v_fma_f32 v17, v17, s101, v34
	v_add_f32_e32 v35, v27, v35
	v_exp_f32_e32 v23, v23
	v_fma_f32 v18, v18, s101, v34
	v_add_f32_e32 v35, v20, v35
	v_exp_f32_e32 v16, v16
	v_fma_f32 v19, v19, s101, v34
	v_add_f32_e32 v35, v21, v35
	v_exp_f32_e32 v17, v17
	v_add_f32_e32 v35, v22, v35
	v_exp_f32_e32 v18, v18
	v_add_f32_e32 v35, v23, v35
	v_exp_f32_e32 v19, v19
	v_add_f32_e32 v34, v16, v35
	v_add_f32_e32 v34, v17, v34
	v_add_f32_e32 v34, v18, v34
	v_add_f32_e32 v34, v19, v34
	ds_bpermute_b32 v35, v171, v34
	s_waitcnt lgkmcnt(0)
	v_add_f32_e32 v34, v34, v35
	ds_bpermute_b32 v35, v172, v34
	s_and_saveexec_b64 s[30:31], vcc
	s_cbranch_execz .LBB0_1019
	s_waitcnt lgkmcnt(0)
	v_add_f32_e32 v34, v34, v35
	ds_write_b32 v173, v34 offset:640
.LBB0_1019:
	s_or_b64 exec, exec, s[30:31]
	v_max_f32_e32 v34, v143, v143
	s_waitcnt lgkmcnt(0)
	v_max_f32_e32 v35, v141, v141
	v_max_f32_e32 v34, v35, v34
	s_lshl_b64 s[28:29], s[28:29], 16
	v_max3_f32 v34, v135, v139, v34
	v_mul_f32_e32 v34, 0xbdb8aa3b, v34
	v_fma_f32 v12, v12, s101, v34
	v_fma_f32 v13, v13, s101, v34
	v_fma_f32 v14, v14, s101, v34
	v_exp_f32_e32 v12, v12
	v_fma_f32 v15, v15, s101, v34
	v_exp_f32_e32 v13, v13
	v_fma_f32 v8, v8, s101, v34
	v_exp_f32_e32 v14, v14
	v_fma_f32 v9, v9, s101, v34
	v_exp_f32_e32 v15, v15
	v_fma_f32 v10, v10, s101, v34
	v_add_f32_e32 v35, 0, v12
	v_exp_f32_e32 v8, v8
	v_fma_f32 v11, v11, s101, v34
	v_add_f32_e32 v35, v13, v35
	v_exp_f32_e32 v9, v9
	v_fma_f32 v4, v4, s101, v34
	v_add_f32_e32 v35, v14, v35
	v_exp_f32_e32 v10, v10
	v_fma_f32 v5, v5, s101, v34
	v_add_f32_e32 v35, v15, v35
	v_exp_f32_e32 v11, v11
	v_fma_f32 v6, v6, s101, v34
	v_add_f32_e32 v35, v8, v35
	v_exp_f32_e32 v4, v4
	v_fma_f32 v7, v7, s101, v34
	v_add_f32_e32 v35, v9, v35
	v_exp_f32_e32 v5, v5
	v_fma_f32 v0, v0, s101, v34
	v_add_f32_e32 v35, v10, v35
	v_exp_f32_e32 v6, v6
	v_fma_f32 v1, v1, s101, v34
	v_add_f32_e32 v35, v11, v35
	v_exp_f32_e32 v7, v7
	v_fma_f32 v2, v2, s101, v34
	v_add_f32_e32 v35, v4, v35
	v_exp_f32_e32 v0, v0
	v_fma_f32 v3, v3, s101, v34
	v_add_f32_e32 v35, v5, v35
	v_exp_f32_e32 v1, v1
	v_add_f32_e32 v35, v6, v35
	v_exp_f32_e32 v2, v2
	v_add_f32_e32 v35, v7, v35
	v_exp_f32_e32 v3, v3
	v_add_f32_e32 v34, v0, v35
	v_add_f32_e32 v34, v1, v34
	v_add_f32_e32 v34, v2, v34
	v_add_f32_e32 v34, v3, v34
	ds_bpermute_b32 v35, v171, v34
	s_waitcnt lgkmcnt(0)
	v_add_f32_e32 v34, v34, v35
	ds_bpermute_b32 v35, v172, v34
	s_and_saveexec_b64 s[30:31], vcc
	s_cbranch_execz .LBB0_1021
	s_waitcnt lgkmcnt(0)
	v_add_f32_e32 v34, v34, v35
	ds_write_b32 v173, v34 offset:704

.LBB0_1067:
	s_mov_b32 s101, 0x3db8aa3b
	s_mov_b32 s99, 0x20400
	v_mov_b32_e32 v14, v136
	s_waitcnt vmcnt(0)
	s_barrier
	s_ashr_i32 s33, s51, 5
	v_bfe_i32 v2, v14, 27, 1
	v_lshlrev_b32_e32 v1, 4, v14
	v_lshrrev_b32_e32 v2, 22, v2
	v_add_u32_e32 v2, v1, v2
	v_and_b32_e32 v2, 0xfffffc00, v2
	v_sub_u32_e32 v2, v1, v2
	v_lshrrev_b32_e32 v3, 4, v2
	v_ashrrev_i32_e32 v0, 31, v14
	v_bitop3_b32 v2, v3, v2, 32 bitop3:0x6c
	v_lshrrev_b32_e32 v0, 26, v0
	v_ashrrev_i32_e32 v4, 31, v2
	v_add_u32_e32 v0, v14, v0
	v_lshrrev_b32_e32 v4, 26, v4
	v_ashrrev_i32_e32 v0, 6, v0
	v_add_u32_e32 v4, v2, v4
	v_lshlrev_b32_e32 v3, 3, v0
	v_ashrrev_i32_e32 v5, 6, v4
	v_and_b32_e32 v4, 0xc0, v4
	v_and_b32_e32 v3, -16, v3
	v_lshlrev_b32_e32 v0, 5, v0
	v_sub_u32_e32 v2, v2, v4
	v_add_u32_e32 v3, v5, v3
	v_and_b32_e32 v0, 32, v0
	v_ashrrev_i16_sdwa v2, v133, sext(v2) dst_sel:DWORD dst_unused:UNUSED_PAD src0_sel:DWORD src1_sel:BYTE_0
	v_add_u32_sdwa v0, v0, sext(v2) dst_sel:DWORD dst_unused:UNUSED_PAD src0_sel:DWORD src1_sel:WORD_0
	v_lshlrev_b32_e32 v2, 11, v3
	v_lshl_add_u32 v0, v0, 1, v2
	v_mad_u64_u32 v[6:7], s[56:57], v3, s37, v[0:1]
	v_add_u32_e32 v1, 0x2000, v1
	v_ashrrev_i32_e32 v2, 31, v1
	v_lshrrev_b32_e32 v2, 22, v2
	v_add_u32_e32 v2, v1, v2
	v_ashrrev_i32_e32 v2, 10, v2
	s_lshl_b32 s28, s33, 11
	s_and_b32 s29, s3, 0x700
	v_mul_i32_i24_e32 v3, 0x400, v2
	s_or_b32 s28, s28, s29
	v_sub_u32_e32 v1, v1, v3
	s_ashr_i32 s29, s28, 31
	v_lshrrev_b32_e32 v3, 4, v1
	s_bfe_u32 s52, s51, 0x20003
	s_lshl_b64 s[30:31], s[28:29], 11
	v_bitop3_b32 v1, v3, v1, 32 bitop3:0x6c
	s_add_u32 s29, s62, s30
	v_ashrrev_i32_e32 v4, 31, v1
	s_addc_u32 s30, s63, s31
	s_lshl_b32 s31, s52, 9
	v_lshrrev_b32_e32 v4, 26, v4
	s_add_u32 s34, s29, s31
	v_add_u32_e32 v4, v1, v4
	s_addc_u32 s35, s30, 0
	s_lshl_b32 s29, s33, 2
	v_lshlrev_b32_e32 v3, 3, v2
	v_ashrrev_i32_e32 v5, 6, v4
	v_and_b32_e32 v4, 0xc0, v4
	s_or_b32 s30, s29, s52
	v_and_b32_e32 v3, -16, v3
	v_lshlrev_b32_e32 v2, 5, v2
	v_sub_u32_e32 v1, v1, v4
	s_ashr_i32 s31, s30, 31
	v_add_u32_e32 v3, v5, v3
	v_and_b32_e32 v2, 32, v2
	v_ashrrev_i16_sdwa v1, v133, sext(v1) dst_sel:DWORD dst_unused:UNUSED_PAD src0_sel:DWORD src1_sel:BYTE_0
	s_lshl_b64 s[40:41], s[30:31], 17
	v_add_u32_sdwa v1, v2, sext(v1) dst_sel:DWORD dst_unused:UNUSED_PAD src0_sel:DWORD src1_sel:WORD_0
	v_lshlrev_b32_e32 v2, 11, v3
	s_add_u32 s40, s64, s40
	v_readfirstlane_b32 s29, v14
	v_lshl_add_u32 v2, v1, 1, v2
	s_addc_u32 s41, s65, s41
	v_mad_u64_u32 v[4:5], s[56:57], v3, s37, v[2:3]
	s_ashr_i32 s53, s29, 6
	s_lshl_b32 s57, s53, 10
	s_add_i32 s76, s57, 0
	s_add_i32 m0, s76, 0x10000
	s_ashr_i32 s33, s29, 8
	global_load_lds_dwordx4 v6, s[40:41]
	s_add_i32 m0, s76, 0x12000
	s_add_i32 s77, s76, 0x2000
	global_load_lds_dwordx4 v4, s[40:41]
	s_mov_b32 m0, s76
	s_add_u32 s68, s40, 0x10000
	global_load_lds_dwordx4 v0, s[34:35]
	s_mov_b32 m0, s77
	s_addc_u32 s69, s41, 0
	global_load_lds_dwordx4 v2, s[34:35]
	s_add_i32 m0, s76, 0x14000
	v_mov_b32_e32 v128, v6
	global_load_lds_dwordx4 v6, s[68:69]
	s_add_i32 m0, s76, 0x16000
	s_add_u32 s72, s34, 0x40000
	global_load_lds_dwordx4 v4, s[68:69]
	s_addc_u32 s73, s35, 0
	s_add_i32 s69, s76, 0x4000
	s_mov_b32 m0, s69
	s_add_i32 s56, s76, 0x6000
	global_load_lds_dwordx4 v0, s[72:73]
	s_mov_b32 m0, s56
	v_mov_b32_e32 v5, v129
	global_load_lds_dwordx4 v2, s[72:73]
	v_mov_b32_e32 v1, v129
	v_mov_b32_e32 v3, v129
	v_lshl_add_u64 v[12:13], s[40:41], 0, v[128:129]
	v_lshl_add_u64 v[10:11], s[40:41], 0, v[4:5]
	v_lshl_add_u64 v[6:7], s[34:35], 0, v[0:1]
	s_cmp_lg_u32 s33, 1
	v_lshl_add_u64 v[8:9], s[34:35], 0, v[2:3]
	s_cbranch_scc1 .LBB0_1069
	s_barrier

.LBB0_1087:
	s_or_b64 exec, exec, s[34:35]
	v_add3_u32 v134, s99, v130, v131
	v_add_u32_e32 v142, 0xc00, v134
	s_waitcnt vmcnt(0) lgkmcnt(0)
	s_barrier
	ds_read2_b32 v[160:161], v134 offset1:16
	v_add_u32_e32 v140, 0x800, v134
	ds_read2_b32 v[166:167], v142 offset1:16
	ds_read2_b32 v[164:165], v140 offset1:16
	v_add_u32_e32 v138, 0x400, v134
	ds_read2_b32 v[162:163], v138 offset1:16
	ds_read2_b32 v[152:153], v134 offset0:32 offset1:48
	ds_read2_b32 v[154:155], v138 offset0:32 offset1:48
	ds_read2_b32 v[156:157], v140 offset0:32 offset1:48
	ds_read2_b32 v[158:159], v142 offset0:32 offset1:48
	ds_read2_b32 v[144:145], v134 offset0:128 offset1:144
	ds_read2_b32 v[146:147], v138 offset0:128 offset1:144
	ds_read2_b32 v[148:149], v140 offset0:128 offset1:144
	ds_read2_b32 v[150:151], v142 offset0:128 offset1:144
	s_waitcnt lgkmcnt(10)
	v_max_f32_e32 v130, v166, v166
	s_waitcnt lgkmcnt(9)
	v_max_f32_e32 v131, v164, v164
	v_max_f32_e32 v130, v131, v130
	s_waitcnt lgkmcnt(8)
	v_max3_f32 v135, v160, v162, v130
	v_mul_f32_e32 v135, 0xbdb8aa3b, v135
	v_fma_f32 v124, v124, s101, v135
	v_fma_f32 v125, v125, s101, v135
	v_fma_f32 v126, v126, s101, v135
	v_exp_f32_e32 v124, v124
	v_fma_f32 v127, v127, s101, v135
	v_exp_f32_e32 v125, v125
	v_exp_f32_e32 v126, v126
	v_exp_f32_e32 v127, v127
	v_add_f32_e32 v130, 0, v124
	v_fma_f32 v116, v116, s101, v135
	v_fma_f32 v118, v118, s101, v135
	v_add_f32_e32 v130, v125, v130
	v_fma_f32 v117, v117, s101, v135
	v_add_f32_e32 v130, v126, v130
	v_add_f32_e32 v139, v127, v130
	v_exp_f32_e32 v116, v116
	v_exp_f32_e32 v130, v118
	v_fma_f32 v118, v119, s101, v135
	v_exp_f32_e32 v117, v117
	v_exp_f32_e32 v131, v118
	v_add_f32_e32 v118, v116, v139
	v_add_f32_e32 v118, v117, v118
	v_add_f32_e32 v118, v130, v118
	v_add_f32_e32 v139, v131, v118
	v_fma_f32 v118, v120, s101, v135
	v_fma_f32 v119, v121, s101, v135
	v_fma_f32 v120, v122, s101, v135
	v_exp_f32_e32 v118, v118
	v_fma_f32 v121, v123, s101, v135
	v_exp_f32_e32 v119, v119
	v_fma_f32 v112, v112, s101, v135
	v_exp_f32_e32 v120, v120
	v_fma_f32 v113, v113, s101, v135
	v_exp_f32_e32 v121, v121
	v_fma_f32 v114, v114, s101, v135
	v_add_f32_e32 v122, v118, v139
	v_exp_f32_e32 v112, v112
	v_fma_f32 v115, v115, s101, v135
	v_add_f32_e32 v122, v119, v122
	v_exp_f32_e32 v113, v113
	v_add_f32_e32 v122, v120, v122
	v_exp_f32_e32 v114, v114
	v_add_f32_e32 v122, v121, v122
	v_exp_f32_e32 v115, v115
	v_add_f32_e32 v122, v112, v122
	v_add_f32_e32 v122, v113, v122
	v_add_f32_e32 v122, v114, v122
	v_add_f32_e32 v122, v115, v122
	ds_bpermute_b32 v123, v171, v122
	ds_read2_b32 v[134:135], v134 offset0:160 offset1:176
	ds_read2_b32 v[138:139], v138 offset0:160 offset1:176
	ds_read2_b32 v[140:141], v140 offset0:160 offset1:176
	ds_read2_b32 v[142:143], v142 offset0:160 offset1:176
	s_waitcnt lgkmcnt(0)
	s_barrier
	v_add_f32_e32 v122, v122, v123
	ds_bpermute_b32 v123, v172, v122
	s_and_saveexec_b64 s[34:35], vcc
	s_cbranch_execz .LBB0_1089
	s_waitcnt lgkmcnt(0)
	v_add_f32_e32 v122, v122, v123
	ds_write_b32 v173, v122
.LBB0_1089:
	s_or_b64 exec, exec, s[34:35]
	v_max_f32_e32 v122, v167, v167
	s_waitcnt lgkmcnt(0)
	v_max_f32_e32 v123, v165, v165
	v_max_f32_e32 v122, v123, v122
	v_max3_f32 v160, v161, v163, v122
	v_mul_f32_e32 v160, 0xbdb8aa3b, v160
	v_fma_f32 v108, v108, s101, v160
	v_fma_f32 v109, v109, s101, v160
	v_fma_f32 v110, v110, s101, v160
	v_exp_f32_e32 v108, v108
	v_fma_f32 v111, v111, s101, v160
	v_exp_f32_e32 v109, v109
	v_exp_f32_e32 v110, v110
	v_exp_f32_e32 v111, v111
	v_add_f32_e32 v122, 0, v108
	v_fma_f32 v100, v100, s101, v160
	v_fma_f32 v102, v102, s101, v160
	v_add_f32_e32 v122, v109, v122
	v_fma_f32 v101, v101, s101, v160
	v_add_f32_e32 v122, v110, v122
	v_add_f32_e32 v161, v111, v122
	v_exp_f32_e32 v100, v100
	v_exp_f32_e32 v122, v102
	v_fma_f32 v102, v103, s101, v160
	v_exp_f32_e32 v101, v101
	v_exp_f32_e32 v123, v102
	v_add_f32_e32 v102, v100, v161
	v_add_f32_e32 v102, v101, v102
	v_add_f32_e32 v102, v122, v102
	v_add_f32_e32 v161, v123, v102
	v_fma_f32 v102, v104, s101, v160
	v_fma_f32 v103, v105, s101, v160
	v_fma_f32 v104, v106, s101, v160
	v_exp_f32_e32 v102, v102
	v_fma_f32 v105, v107, s101, v160
	v_exp_f32_e32 v103, v103
	v_fma_f32 v96, v96, s101, v160
	v_exp_f32_e32 v104, v104
	v_fma_f32 v97, v97, s101, v160
	v_exp_f32_e32 v105, v105
	v_fma_f32 v98, v98, s101, v160
	v_add_f32_e32 v106, v102, v161
	v_exp_f32_e32 v96, v96
	v_fma_f32 v99, v99, s101, v160
	v_add_f32_e32 v106, v103, v106
	v_exp_f32_e32 v97, v97
	v_add_f32_e32 v106, v104, v106
	v_exp_f32_e32 v98, v98
	v_add_f32_e32 v106, v105, v106
	v_exp_f32_e32 v99, v99
	v_add_f32_e32 v106, v96, v106
	v_add_f32_e32 v106, v97, v106
	v_add_f32_e32 v106, v98, v106
	v_add_f32_e32 v106, v99, v106
	ds_bpermute_b32 v107, v171, v106
	s_waitcnt lgkmcnt(0)
	v_add_f32_e32 v106, v106, v107
	ds_bpermute_b32 v107, v172, v106
	s_and_saveexec_b64 s[34:35], vcc
	s_cbranch_execz .LBB0_1091
	s_waitcnt lgkmcnt(0)
	v_add_f32_e32 v106, v106, v107
	ds_write_b32 v173, v106 offset:64
.LBB0_1091:
	s_or_b64 exec, exec, s[34:35]
	v_max_f32_e32 v106, v158, v158
	s_waitcnt lgkmcnt(0)
	v_max_f32_e32 v107, v156, v156
	v_max_f32_e32 v106, v107, v106
	v_max3_f32 v152, v152, v154, v106
	v_mul_f32_e32 v152, 0xbdb8aa3b, v152
	v_fma_f32 v92, v92, s101, v152
	v_fma_f32 v93, v93, s101, v152
	v_fma_f32 v94, v94, s101, v152
	v_exp_f32_e32 v92, v92
	v_fma_f32 v95, v95, s101, v152
	v_exp_f32_e32 v93, v93
	v_exp_f32_e32 v94, v94
	v_exp_f32_e32 v95, v95
	v_add_f32_e32 v106, 0, v92
	v_fma_f32 v84, v84, s101, v152
	v_fma_f32 v86, v86, s101, v152
	v_add_f32_e32 v106, v93, v106
	v_fma_f32 v85, v85, s101, v152
	v_add_f32_e32 v106, v94, v106
	v_add_f32_e32 v154, v95, v106
	v_exp_f32_e32 v84, v84
	v_exp_f32_e32 v106, v86
	v_fma_f32 v86, v87, s101, v152
	v_exp_f32_e32 v85, v85
	v_exp_f32_e32 v107, v86
	v_add_f32_e32 v86, v84, v154
	v_add_f32_e32 v86, v85, v86
	v_add_f32_e32 v86, v106, v86
	v_add_f32_e32 v154, v107, v86
	v_fma_f32 v86, v88, s101, v152
	v_fma_f32 v87, v89, s101, v152
	v_fma_f32 v88, v90, s101, v152
	v_exp_f32_e32 v86, v86
	v_fma_f32 v89, v91, s101, v152
	v_exp_f32_e32 v87, v87
	v_fma_f32 v80, v80, s101, v152
	v_exp_f32_e32 v88, v88
	v_fma_f32 v81, v81, s101, v152
	v_exp_f32_e32 v89, v89
	v_fma_f32 v82, v82, s101, v152
	v_add_f32_e32 v90, v86, v154
	v_exp_f32_e32 v80, v80
	v_fma_f32 v83, v83, s101, v152
	v_add_f32_e32 v90, v87, v90
	v_exp_f32_e32 v81, v81
	v_add_f32_e32 v90, v88, v90
	v_exp_f32_e32 v82, v82
	v_add_f32_e32 v90, v89, v90
	v_exp_f32_e32 v83, v83
	v_add_f32_e32 v90, v80, v90
	v_add_f32_e32 v90, v81, v90
	v_add_f32_e32 v90, v82, v90
	v_add_f32_e32 v90, v83, v90
	ds_bpermute_b32 v91, v171, v90
	s_waitcnt lgkmcnt(0)
	v_add_f32_e32 v90, v90, v91
	ds_bpermute_b32 v91, v172, v90
	s_and_saveexec_b64 s[34:35], vcc
	s_cbranch_execz .LBB0_1093
	s_waitcnt lgkmcnt(0)
	v_add_f32_e32 v90, v90, v91
	ds_write_b32 v173, v90 offset:128
.LBB0_1093:
	s_or_b64 exec, exec, s[34:35]
	v_max_f32_e32 v90, v159, v159
	s_waitcnt lgkmcnt(0)
	v_max_f32_e32 v91, v157, v157
	v_max_f32_e32 v90, v91, v90
	v_max3_f32 v152, v153, v155, v90
	v_mul_f32_e32 v152, 0xbdb8aa3b, v152
	v_fma_f32 v76, v76, s101, v152
	v_fma_f32 v77, v77, s101, v152
	v_fma_f32 v78, v78, s101, v152
	v_exp_f32_e32 v76, v76
	v_fma_f32 v79, v79, s101, v152
	v_exp_f32_e32 v77, v77
	v_exp_f32_e32 v78, v78
	v_exp_f32_e32 v79, v79
	v_add_f32_e32 v90, 0, v76
	v_fma_f32 v68, v68, s101, v152
	v_fma_f32 v70, v70, s101, v152
	v_add_f32_e32 v90, v77, v90
	v_fma_f32 v69, v69, s101, v152
	v_add_f32_e32 v90, v78, v90
	v_add_f32_e32 v153, v79, v90
	v_exp_f32_e32 v68, v68
	v_exp_f32_e32 v90, v70
	v_fma_f32 v70, v71, s101, v152
	v_exp_f32_e32 v69, v69
	v_exp_f32_e32 v91, v70
	v_add_f32_e32 v70, v68, v153
	v_add_f32_e32 v70, v69, v70
	v_add_f32_e32 v70, v90, v70
	v_add_f32_e32 v153, v91, v70
	v_fma_f32 v70, v72, s101, v152
	v_fma_f32 v71, v73, s101, v152
	v_fma_f32 v72, v74, s101, v152
	v_exp_f32_e32 v70, v70
	v_fma_f32 v73, v75, s101, v152
	v_exp_f32_e32 v71, v71
	v_fma_f32 v64, v64, s101, v152
	v_exp_f32_e32 v72, v72
	v_fma_f32 v65, v65, s101, v152
	v_exp_f32_e32 v73, v73
	v_fma_f32 v66, v66, s101, v152
	v_add_f32_e32 v74, v70, v153
	v_exp_f32_e32 v64, v64
	v_fma_f32 v67, v67, s101, v152
	v_add_f32_e32 v74, v71, v74
	v_exp_f32_e32 v65, v65
	v_add_f32_e32 v74, v72, v74
	v_exp_f32_e32 v66, v66
	v_add_f32_e32 v74, v73, v74
	v_exp_f32_e32 v67, v67
	v_add_f32_e32 v74, v64, v74
	v_add_f32_e32 v74, v65, v74
	v_add_f32_e32 v74, v66, v74
	v_add_f32_e32 v74, v67, v74
	ds_bpermute_b32 v75, v171, v74
	s_waitcnt lgkmcnt(0)
	v_add_f32_e32 v74, v74, v75
	ds_bpermute_b32 v75, v172, v74
	s_and_saveexec_b64 s[34:35], vcc
	s_cbranch_execz .LBB0_1095
	s_waitcnt lgkmcnt(0)
	v_add_f32_e32 v74, v74, v75
	ds_write_b32 v173, v74 offset:192
.LBB0_1095:
	s_or_b64 exec, exec, s[34:35]
	v_max_f32_e32 v74, v150, v150
	s_waitcnt lgkmcnt(0)
	v_max_f32_e32 v75, v148, v148
	v_max_f32_e32 v74, v75, v74
	v_max3_f32 v74, v144, v146, v74
	v_mul_f32_e32 v74, 0xbdb8aa3b, v74
	v_fma_f32 v60, v60, s101, v74
	v_fma_f32 v61, v61, s101, v74
	v_fma_f32 v62, v62, s101, v74
	v_exp_f32_e32 v60, v60
	v_fma_f32 v63, v63, s101, v74
	v_exp_f32_e32 v61, v61
	v_fma_f32 v56, v56, s101, v74
	v_exp_f32_e32 v62, v62
	v_fma_f32 v57, v57, s101, v74
	v_exp_f32_e32 v63, v63
	v_fma_f32 v58, v58, s101, v74
	v_add_f32_e32 v75, 0, v60
	v_exp_f32_e32 v56, v56
	v_fma_f32 v59, v59, s101, v74
	v_add_f32_e32 v75, v61, v75
	v_exp_f32_e32 v57, v57
	v_fma_f32 v52, v52, s101, v74
	v_add_f32_e32 v75, v62, v75
	v_exp_f32_e32 v58, v58
	v_fma_f32 v53, v53, s101, v74
	v_add_f32_e32 v75, v63, v75
	v_exp_f32_e32 v59, v59
	v_fma_f32 v54, v54, s101, v74
	v_add_f32_e32 v75, v56, v75
	v_exp_f32_e32 v52, v52
	v_fma_f32 v55, v55, s101, v74
	v_add_f32_e32 v75, v57, v75
	v_exp_f32_e32 v53, v53
	v_fma_f32 v48, v48, s101, v74
	v_add_f32_e32 v75, v58, v75
	v_exp_f32_e32 v54, v54
	v_fma_f32 v49, v49, s101, v74
	v_add_f32_e32 v75, v59, v75
	v_exp_f32_e32 v55, v55
	v_fma_f32 v50, v50, s101, v74
	v_add_f32_e32 v75, v52, v75
	v_exp_f32_e32 v48, v48
	v_fma_f32 v51, v51, s101, v74
	v_add_f32_e32 v75, v53, v75
	v_exp_f32_e32 v49, v49
	v_add_f32_e32 v75, v54, v75
	v_exp_f32_e32 v50, v50
	v_add_f32_e32 v75, v55, v75
	v_exp_f32_e32 v51, v51
	v_add_f32_e32 v74, v48, v75
	v_add_f32_e32 v74, v49, v74
	v_add_f32_e32 v74, v50, v74
	v_add_f32_e32 v74, v51, v74
	ds_bpermute_b32 v75, v171, v74
	s_waitcnt lgkmcnt(0)
	v_add_f32_e32 v74, v74, v75
	ds_bpermute_b32 v75, v172, v74
	s_and_saveexec_b64 s[34:35], vcc
	s_cbranch_execz .LBB0_1097
	s_waitcnt lgkmcnt(0)
	v_add_f32_e32 v74, v74, v75
	ds_write_b32 v173, v74 offset:512
.LBB0_1097:
	s_or_b64 exec, exec, s[34:35]
	v_max_f32_e32 v74, v151, v151
	s_waitcnt lgkmcnt(0)
	v_max_f32_e32 v75, v149, v149
	v_max_f32_e32 v74, v75, v74
	v_max3_f32 v74, v145, v147, v74
	v_mul_f32_e32 v74, 0xbdb8aa3b, v74
	v_fma_f32 v44, v44, s101, v74
	v_fma_f32 v45, v45, s101, v74
	v_fma_f32 v46, v46, s101, v74
	v_exp_f32_e32 v44, v44
	v_fma_f32 v47, v47, s101, v74
	v_exp_f32_e32 v45, v45
	v_fma_f32 v40, v40, s101, v74
	v_exp_f32_e32 v46, v46
	v_fma_f32 v41, v41, s101, v74
	v_exp_f32_e32 v47, v47
	v_fma_f32 v42, v42, s101, v74
	v_add_f32_e32 v75, 0, v44
	v_exp_f32_e32 v40, v40
	v_fma_f32 v43, v43, s101, v74
	v_add_f32_e32 v75, v45, v75
	v_exp_f32_e32 v41, v41
	v_fma_f32 v36, v36, s101, v74
	v_add_f32_e32 v75, v46, v75
	v_exp_f32_e32 v42, v42
	v_fma_f32 v37, v37, s101, v74
	v_add_f32_e32 v75, v47, v75
	v_exp_f32_e32 v43, v43
	v_fma_f32 v38, v38, s101, v74
	v_add_f32_e32 v75, v40, v75
	v_exp_f32_e32 v36, v36
	v_fma_f32 v39, v39, s101, v74
	v_add_f32_e32 v75, v41, v75
	v_exp_f32_e32 v37, v37
	v_fma_f32 v32, v32, s101, v74
	v_add_f32_e32 v75, v42, v75
	v_exp_f32_e32 v38, v38
	v_fma_f32 v33, v33, s101, v74
	v_add_f32_e32 v75, v43, v75
	v_exp_f32_e32 v39, v39
	v_fma_f32 v34, v34, s101, v74
	v_add_f32_e32 v75, v36, v75
	v_exp_f32_e32 v32, v32
	v_fma_f32 v35, v35, s101, v74
	v_add_f32_e32 v75, v37, v75
	v_exp_f32_e32 v33, v33
	v_add_f32_e32 v75, v38, v75
	v_exp_f32_e32 v34, v34
	v_add_f32_e32 v75, v39, v75
	v_exp_f32_e32 v35, v35
	v_add_f32_e32 v74, v32, v75
	v_add_f32_e32 v74, v33, v74
	v_add_f32_e32 v74, v34, v74
	v_add_f32_e32 v74, v35, v74
	ds_bpermute_b32 v75, v171, v74
	s_waitcnt lgkmcnt(0)
	v_add_f32_e32 v74, v74, v75
	ds_bpermute_b32 v75, v172, v74
	s_and_saveexec_b64 s[34:35], vcc
	s_cbranch_execz .LBB0_1099
	s_waitcnt lgkmcnt(0)
	v_add_f32_e32 v74, v74, v75
	ds_write_b32 v173, v74 offset:576
.LBB0_1099:
	s_or_b64 exec, exec, s[34:35]
	v_max_f32_e32 v74, v142, v142
	s_waitcnt lgkmcnt(0)
	v_max_f32_e32 v75, v140, v140
	v_max_f32_e32 v74, v75, v74
	v_max3_f32 v74, v134, v138, v74
	v_mul_f32_e32 v74, 0xbdb8aa3b, v74
	v_fma_f32 v28, v28, s101, v74
	v_fma_f32 v29, v29, s101, v74
	v_fma_f32 v30, v30, s101, v74
	v_exp_f32_e32 v28, v28
	v_fma_f32 v31, v31, s101, v74
	v_exp_f32_e32 v29, v29
	v_fma_f32 v24, v24, s101, v74
	v_exp_f32_e32 v30, v30
	v_fma_f32 v25, v25, s101, v74
	v_exp_f32_e32 v31, v31
	v_fma_f32 v26, v26, s101, v74
	v_add_f32_e32 v75, 0, v28
	v_exp_f32_e32 v24, v24
	v_fma_f32 v27, v27, s101, v74
	v_add_f32_e32 v75, v29, v75
	v_exp_f32_e32 v25, v25
	v_fma_f32 v20, v20, s101, v74
	v_add_f32_e32 v75, v30, v75
	v_exp_f32_e32 v26, v26
	v_fma_f32 v21, v21, s101, v74
	v_add_f32_e32 v75, v31, v75
	v_exp_f32_e32 v27, v27
	v_fma_f32 v22, v22, s101, v74
	v_add_f32_e32 v75, v24, v75
	v_exp_f32_e32 v20, v20
	v_fma_f32 v23, v23, s101, v74
	v_add_f32_e32 v75, v25, v75
	v_exp_f32_e32 v21, v21
	v_fma_f32 v16, v16, s101, v74
	v_add_f32_e32 v75, v26, v75
	v_exp_f32_e32 v22, v22
	v_fma_f32 v17, v17, s101, v74
	v_add_f32_e32 v75, v27, v75
	v_exp_f32_e32 v23, v23
	v_fma_f32 v18, v18, s101, v74
	v_add_f32_e32 v75, v20, v75
	v_exp_f32_e32 v16, v16
	v_fma_f32 v19, v19, s101, v74
	v_add_f32_e32 v75, v21, v75
	v_exp_f32_e32 v17, v17
	v_add_f32_e32 v75, v22, v75
	v_exp_f32_e32 v18, v18
	v_add_f32_e32 v75, v23, v75
	v_exp_f32_e32 v19, v19
	v_add_f32_e32 v74, v16, v75
	v_add_f32_e32 v74, v17, v74
	v_add_f32_e32 v74, v18, v74
	v_add_f32_e32 v74, v19, v74
	ds_bpermute_b32 v75, v171, v74
	s_waitcnt lgkmcnt(0)
	v_add_f32_e32 v74, v74, v75
	ds_bpermute_b32 v75, v172, v74
	s_and_saveexec_b64 s[34:35], vcc
	s_cbranch_execz .LBB0_1101
	s_waitcnt lgkmcnt(0)
	v_add_f32_e32 v74, v74, v75
	ds_write_b32 v173, v74 offset:640
.LBB0_1101:
	s_or_b64 exec, exec, s[34:35]
	v_max_f32_e32 v74, v143, v143
	s_waitcnt lgkmcnt(0)
	v_max_f32_e32 v75, v141, v141
	v_max_f32_e32 v74, v75, v74
	s_lshl_b64 s[30:31], s[30:31], 16
	v_max3_f32 v74, v135, v139, v74
	v_mul_f32_e32 v74, 0xbdb8aa3b, v74
	v_fma_f32 v12, v12, s101, v74
	v_fma_f32 v13, v13, s101, v74
	v_fma_f32 v14, v14, s101, v74
	v_exp_f32_e32 v12, v12
	v_fma_f32 v15, v15, s101, v74
	v_exp_f32_e32 v13, v13
	v_fma_f32 v8, v8, s101, v74
	v_exp_f32_e32 v14, v14
	v_fma_f32 v9, v9, s101, v74
	v_exp_f32_e32 v15, v15
	v_fma_f32 v10, v10, s101, v74
	v_add_f32_e32 v75, 0, v12
	v_exp_f32_e32 v8, v8
	v_fma_f32 v11, v11, s101, v74
	v_add_f32_e32 v75, v13, v75
	v_exp_f32_e32 v9, v9
	v_fma_f32 v4, v4, s101, v74
	v_add_f32_e32 v75, v14, v75
	v_exp_f32_e32 v10, v10
	v_fma_f32 v5, v5, s101, v74
	v_add_f32_e32 v75, v15, v75
	v_exp_f32_e32 v11, v11
	v_fma_f32 v6, v6, s101, v74
	v_add_f32_e32 v75, v8, v75
	v_exp_f32_e32 v4, v4
	v_fma_f32 v7, v7, s101, v74
	v_add_f32_e32 v75, v9, v75
	v_exp_f32_e32 v5, v5
	v_fma_f32 v0, v0, s101, v74
	v_add_f32_e32 v75, v10, v75
	v_exp_f32_e32 v6, v6
	v_fma_f32 v1, v1, s101, v74
	v_add_f32_e32 v75, v11, v75
	v_exp_f32_e32 v7, v7
	v_fma_f32 v2, v2, s101, v74
	v_add_f32_e32 v75, v4, v75
	v_exp_f32_e32 v0, v0
	v_fma_f32 v3, v3, s101, v74
	v_add_f32_e32 v75, v5, v75
	v_exp_f32_e32 v1, v1
	v_add_f32_e32 v75, v6, v75
	v_exp_f32_e32 v2, v2
	v_add_f32_e32 v75, v7, v75
	v_exp_f32_e32 v3, v3
	v_add_f32_e32 v74, v0, v75
	v_add_f32_e32 v74, v1, v74
	v_add_f32_e32 v74, v2, v74
	v_add_f32_e32 v74, v3, v74
	ds_bpermute_b32 v75, v171, v74
	s_waitcnt lgkmcnt(0)
	v_add_f32_e32 v74, v74, v75
	ds_bpermute_b32 v75, v172, v74
	s_and_saveexec_b64 s[34:35], vcc
	s_cbranch_execz .LBB0_1103
	s_waitcnt lgkmcnt(0)
	v_add_f32_e32 v74, v74, v75
	ds_write_b32 v173, v74 offset:704
